# full stack plus phase-6 epilogue loads in K stage 14 and DPP row sums in the conv LayerNorm loop
# speedup vs baseline: 1.0175x; 1.0036x over previous
.LBB0_513:
	ds_read_b128 v[38:41], v23
	ds_read_b128 v[42:45], v23 offset:16
	v_add_u32_e32 v48, 4, v37
	v_add_u32_e32 v46, s2, v37
	v_cmp_lt_u32_e32 vcc, 27, v37
	v_mov_b32_e32 v37, v48
	s_waitcnt lgkmcnt(1)
	v_add_f32_e32 v48, 0, v38
	v_add_f32_e32 v48, v48, v39
	v_add_f32_e32 v48, v48, v40
	v_add_f32_e32 v48, v48, v41
	s_waitcnt lgkmcnt(0)
	v_add_f32_e32 v48, v48, v42
	v_add_f32_e32 v48, v48, v43
	v_add_f32_e32 v48, v48, v44
	v_add_f32_e32 v48, v48, v45
	s_nop 1
	v_add_f32_dpp v48, v48, v48 quad_perm:[1,0,3,2] row_mask:0xf bank_mask:0xf
	s_nop 1
	v_add_f32_dpp v48, v48, v48 quad_perm:[2,3,0,1] row_mask:0xf bank_mask:0xf
	s_nop 1
	v_add_f32_dpp v48, v48, v48 row_half_mirror row_mask:0xf bank_mask:0xf
	s_nop 1
	v_add_f32_dpp v48, v48, v48 row_mirror row_mask:0xf bank_mask:0xf
	s_nop 1
	v_readlane_b32 s99, v48, 0
	v_readlane_b32 s100, v48, 16
	v_readlane_b32 s101, v48, 32
	v_readlane_b32 s32, v48, 48
	v_mov_b32_e32 v49, s99
	v_add_f32_e32 v49, s100, v49
	v_add_f32_e32 v49, s101, v49
	v_add_f32_e32 v48, s32, v49
	global_load_dwordx4 v[2:5], v[24:25], off offset:16
	global_load_dwordx4 v[10:13], v[24:25], off
	global_load_dwordx4 v[6:9], v[26:27], off offset:16
	global_load_dwordx4 v[14:17], v[26:27], off
	s_mov_b32 s3, 0x800000
	s_or_b64 s[0:1], vcc, s[0:1]
	v_ashrrev_i32_e32 v47, 31, v46
	v_lshlrev_b64 v[46:47], 10, v[46:47]
	v_add_u32_e32 v23, 0x2000, v23
	v_lshl_add_u64 v[46:47], v[20:21], 0, v[46:47]
	v_mul_f32_e32 v48, 0x3b000000, v48
	v_pk_add_f32 v[38:39], v[38:39], v[48:49] op_sel_hi:[1,0] neg_lo:[0,1] neg_hi:[0,1]
	v_pk_add_f32 v[40:41], v[40:41], v[48:49] op_sel_hi:[1,0] neg_lo:[0,1] neg_hi:[0,1]
	v_pk_add_f32 v[42:43], v[42:43], v[48:49] op_sel_hi:[1,0] neg_lo:[0,1] neg_hi:[0,1]
	v_pk_add_f32 v[44:45], v[44:45], v[48:49] op_sel_hi:[1,0] neg_lo:[0,1] neg_hi:[0,1]
	v_pk_mul_f32 v[48:49], v[38:39], v[38:39]
	v_pk_mul_f32 v[50:51], v[40:41], v[40:41]
	v_add_f32_e32 v48, v48, v49
	v_add_f32_e32 v48, v50, v48
	v_pk_mul_f32 v[52:53], v[42:43], v[42:43]
	v_add_f32_e32 v48, v51, v48
	v_add_f32_e32 v48, v52, v48
	v_pk_mul_f32 v[54:55], v[44:45], v[44:45]
	v_add_f32_e32 v48, v53, v48
	v_add_f32_e32 v48, v54, v48
	v_add_f32_e32 v48, v55, v48
	s_nop 1
	v_add_f32_dpp v48, v48, v48 quad_perm:[1,0,3,2] row_mask:0xf bank_mask:0xf
	s_nop 1
	v_add_f32_dpp v48, v48, v48 quad_perm:[2,3,0,1] row_mask:0xf bank_mask:0xf
	s_nop 1
	v_add_f32_dpp v48, v48, v48 row_half_mirror row_mask:0xf bank_mask:0xf
	s_nop 1
	v_add_f32_dpp v48, v48, v48 row_mirror row_mask:0xf bank_mask:0xf
	s_nop 1
	v_readlane_b32 s99, v48, 0
	v_readlane_b32 s100, v48, 16
	v_readlane_b32 s101, v48, 32
	v_readlane_b32 s32, v48, 48
	v_mov_b32_e32 v49, s99
	v_add_f32_e32 v49, s100, v49
	v_add_f32_e32 v49, s101, v49
	v_add_f32_e32 v48, s32, v49
	v_fmamk_f32 v48, v48, 0x3b000000, v30
	v_mul_f32_e32 v49, 0x4b800000, v48
	v_cmp_gt_f32_e32 vcc, s3, v48
	s_nop 1
	v_cndmask_b32_e32 v48, v48, v49, vcc
	v_rsq_f32_e32 v48, v48
	s_nop 0
	v_mul_f32_e32 v49, 0x45800000, v48
	v_cndmask_b32_e32 v48, v48, v49, vcc
	v_pk_mul_f32 v[38:39], v[38:39], v[48:49] op_sel_hi:[1,0]
	v_pk_mul_f32 v[40:41], v[40:41], v[48:49] op_sel_hi:[1,0]
	v_pk_mul_f32 v[42:43], v[42:43], v[48:49] op_sel_hi:[1,0]
	v_pk_mul_f32 v[44:45], v[44:45], v[48:49] op_sel_hi:[1,0]
	s_waitcnt vmcnt(0)
	v_pk_fma_f32 v[10:11], v[10:11], v[38:39], v[14:15]
	v_pk_fma_f32 v[12:13], v[12:13], v[40:41], v[16:17]
	v_pk_fma_f32 v[2:3], v[2:3], v[42:43], v[6:7]
	v_pk_fma_f32 v[4:5], v[4:5], v[44:45], v[8:9]
	v_mul_f32_e32 v6, 0xbfb8aa3b, v10
	v_mul_f32_e32 v7, 0xbfb8aa3b, v11
	v_mul_f32_e32 v8, 0xbfb8aa3b, v12
	v_mul_f32_e32 v9, 0xbfb8aa3b, v13
	v_mul_f32_e32 v14, 0xbfb8aa3b, v2
	v_mul_f32_e32 v15, 0xbfb8aa3b, v3
	v_mul_f32_e32 v16, 0xbfb8aa3b, v4
	v_mul_f32_e32 v17, 0xbfb8aa3b, v5
	v_exp_f32_e32 v6, v6
	v_exp_f32_e32 v7, v7
	v_exp_f32_e32 v8, v8
	v_exp_f32_e32 v9, v9
	v_exp_f32_e32 v14, v14
	v_exp_f32_e32 v15, v15
	v_exp_f32_e32 v16, v16
	v_exp_f32_e32 v17, v17
	v_add_f32_e32 v6, 1.0, v6
	v_add_f32_e32 v7, 1.0, v7
	v_add_f32_e32 v8, 1.0, v8
	v_add_f32_e32 v9, 1.0, v9
	v_add_f32_e32 v14, 1.0, v14
	v_add_f32_e32 v15, 1.0, v15
	v_add_f32_e32 v16, 1.0, v16
	v_add_f32_e32 v17, 1.0, v17
	v_rcp_f32_e32 v6, v6
	v_rcp_f32_e32 v7, v7
	v_rcp_f32_e32 v8, v8
	v_rcp_f32_e32 v9, v9
	v_rcp_f32_e32 v14, v14
	v_rcp_f32_e32 v15, v15
	v_rcp_f32_e32 v16, v16
	v_rcp_f32_e32 v17, v17
	v_pk_mul_f32 v[6:7], v[10:11], v[6:7]
	v_pk_mul_f32 v[8:9], v[12:13], v[8:9]
	v_pk_mul_f32 v[10:11], v[2:3], v[14:15]
	v_pk_mul_f32 v[12:13], v[4:5], v[16:17]
	v_cvt_pk_bf16_f32 v2, v6, v7
	v_cvt_pk_bf16_f32 v3, v8, v9
	v_cvt_pk_bf16_f32 v4, v10, v11
	v_cvt_pk_bf16_f32 v5, v12, v13
	global_store_dwordx4 v[46:47], v[2:5], off
	s_andn2_b64 exec, exec, s[0:1]
	s_cbranch_execnz .LBB0_513
	s_or_b64 exec, exec, s[0:1]
	v_readlane_b32 s0, v235, 8
	v_readlane_b32 s1, v235, 12
	s_add_i32 s1, s1, s0
	s_add_i32 s4, s4, s0
	v_readlane_b32 s52, v236, 3
	s_cmpk_gt_i32 s1, 0x1ff
	v_readlane_b32 s53, v236, 4
	s_cbranch_scc0 .LBB0_450
